# two queries per pass in the radix-select top-k (unrolled 31 bit steps)
# speedup vs baseline: 1.0213x; 1.0068x over previous
; #define LAS __attribute__((address_space(3)))
; DI void nsa_unit(LAS char* lds, int b, int g, int qb, const bf16* Z, const bf16* KC, const bf16* VC, bf16* On, int tid, int lane, int wave) {
;     ...
;         for (int qi = 0; qi < 8; ++qi) {
;             const int q = wave * 8 + qi;
;             float v = -INFINITY;
;             if (n <= qb) {
;                 v = ((impH[(0 * 64 + q) * 64 + n] + impH[(1 * 64 + q) * 64 + n]) + impH[(2 * 64 + q) * 64 + n]) + impH[(3 * 64 + q) * 64 + n];
;                 if (n == 0 || n == qb || n == qb - 1) v = 1e6f;
;             }
;             LAS float* vs = (LAS float*)(lds + ATT_SEL_OFF + 512) + wave * 64;
;             vs[n] = v;
;             int cnt = 0;
; #pragma unroll 4
;             for (int m4 = 0; m4 < 16; ++m4) {
;                 const f32x4 vm = *(const LAS f32x4*)(vs + 4 * m4);
; #pragma unroll
;                 for (int e = 0; e < 4; ++e) { const int m = 4 * m4 + e; cnt += (vm[e] > v || (vm[e] == v && m < n)) ? 1 : 0; }
;             }
;             const bool sel = (cnt < 16) && (n <= qb);
;             const unsigned long long mk = __ballot(sel);
.LBB0_1084:
	s_add_i32 s30, s29, s65
	v_mov_b32_e32 v0, 0xff800000
	v_mov_b32_e32 v37, 0xff800000
	s_and_saveexec_b64 s[18:19], s[16:17]
	s_cbranch_execz .Ltk_vals
	s_lshl_b32 s20, s30, 8
	s_add_i32 s21, s20, 0xc000
	v_add_u32_e32 v0, s20, v220
	v_add_u32_e32 v36, s21, v220
	ds_read2st64_b32 v[34:35], v36 offset0:64 offset1:128
	ds_read_b32 v0, v0 offset:49152
	ds_read_b32 v36, v36 offset:49152
	s_add_i32 s20, s20, 0x100
	s_add_i32 s21, s21, 0x100
	v_add_u32_e32 v37, s20, v220
	v_add_u32_e32 v229, s21, v220
	ds_read2st64_b32 v[38:39], v229 offset0:64 offset1:128
	ds_read_b32 v37, v37 offset:49152
	ds_read_b32 v229, v229 offset:49152
	s_waitcnt lgkmcnt(4)
	v_add_f32_e32 v0, v0, v34
	v_add_f32_e32 v0, v0, v35
	s_waitcnt lgkmcnt(3)
	v_add_f32_e32 v0, v0, v36
	s_waitcnt lgkmcnt(1)
	v_add_f32_e32 v37, v37, v38
	v_add_f32_e32 v37, v37, v39
	s_waitcnt lgkmcnt(0)
	v_add_f32_e32 v37, v37, v229
	v_mov_b32_e32 v34, 0x49742400
	v_cndmask_b32_e64 v0, v0, v34, s[12:13]
	v_cndmask_b32_e64 v37, v37, v34, s[12:13]
.Ltk_vals:
	s_or_b64 exec, exec, s[18:19]
	v_cndmask_b32_e64 v34, 0, v0, s[16:17]
	v_cndmask_b32_e64 v38, 0, v37, s[16:17]
	s_mov_b32 s31, 0
	s_mov_b32 s67, 0
	s_or_b32 s52, s31, 0x40000000
	s_or_b32 s98, s67, 0x40000000
	v_cmp_le_u32_e32 vcc, s52, v34
	v_cmp_le_u32_e64 s[100:101], s98, v38
	s_bcnt1_i32_b64 s51, vcc
	s_bcnt1_i32_b64 s99, s[100:101]
	s_cmp_ge_u32 s51, 16
	s_cselect_b32 s31, s52, s31
	s_cmp_ge_u32 s99, 16
	s_cselect_b32 s67, s98, s67
	s_or_b32 s52, s31, 0x20000000
	s_or_b32 s98, s67, 0x20000000
	v_cmp_le_u32_e32 vcc, s52, v34
	v_cmp_le_u32_e64 s[100:101], s98, v38
	s_bcnt1_i32_b64 s51, vcc
	s_bcnt1_i32_b64 s99, s[100:101]
	s_cmp_ge_u32 s51, 16
	s_cselect_b32 s31, s52, s31
	s_cmp_ge_u32 s99, 16
	s_cselect_b32 s67, s98, s67
	s_or_b32 s52, s31, 0x10000000
	s_or_b32 s98, s67, 0x10000000
	v_cmp_le_u32_e32 vcc, s52, v34
	v_cmp_le_u32_e64 s[100:101], s98, v38
	s_bcnt1_i32_b64 s51, vcc
	s_bcnt1_i32_b64 s99, s[100:101]
	s_cmp_ge_u32 s51, 16
	s_cselect_b32 s31, s52, s31
	s_cmp_ge_u32 s99, 16
	s_cselect_b32 s67, s98, s67
	s_or_b32 s52, s31, 0x8000000
	s_or_b32 s98, s67, 0x8000000
	v_cmp_le_u32_e32 vcc, s52, v34
	v_cmp_le_u32_e64 s[100:101], s98, v38
	s_bcnt1_i32_b64 s51, vcc
	s_bcnt1_i32_b64 s99, s[100:101]
	s_cmp_ge_u32 s51, 16
	s_cselect_b32 s31, s52, s31
	s_cmp_ge_u32 s99, 16
	s_cselect_b32 s67, s98, s67
	s_or_b32 s52, s31, 0x4000000
	s_or_b32 s98, s67, 0x4000000
	v_cmp_le_u32_e32 vcc, s52, v34
	v_cmp_le_u32_e64 s[100:101], s98, v38
	s_bcnt1_i32_b64 s51, vcc
	s_bcnt1_i32_b64 s99, s[100:101]
	s_cmp_ge_u32 s51, 16
	s_cselect_b32 s31, s52, s31
	s_cmp_ge_u32 s99, 16
	s_cselect_b32 s67, s98, s67
	s_or_b32 s52, s31, 0x2000000
	s_or_b32 s98, s67, 0x2000000
	v_cmp_le_u32_e32 vcc, s52, v34
	v_cmp_le_u32_e64 s[100:101], s98, v38
	s_bcnt1_i32_b64 s51, vcc
	s_bcnt1_i32_b64 s99, s[100:101]
	s_cmp_ge_u32 s51, 16
	s_cselect_b32 s31, s52, s31
	s_cmp_ge_u32 s99, 16
	s_cselect_b32 s67, s98, s67
	s_or_b32 s52, s31, 0x1000000
	s_or_b32 s98, s67, 0x1000000
	v_cmp_le_u32_e32 vcc, s52, v34
	v_cmp_le_u32_e64 s[100:101], s98, v38
	s_bcnt1_i32_b64 s51, vcc
	s_bcnt1_i32_b64 s99, s[100:101]
	s_cmp_ge_u32 s51, 16
	s_cselect_b32 s31, s52, s31
	s_cmp_ge_u32 s99, 16
	s_cselect_b32 s67, s98, s67
	s_or_b32 s52, s31, 0x800000
	s_or_b32 s98, s67, 0x800000
	v_cmp_le_u32_e32 vcc, s52, v34
	v_cmp_le_u32_e64 s[100:101], s98, v38
	s_bcnt1_i32_b64 s51, vcc
	s_bcnt1_i32_b64 s99, s[100:101]
	s_cmp_ge_u32 s51, 16
	s_cselect_b32 s31, s52, s31
	s_cmp_ge_u32 s99, 16
	s_cselect_b32 s67, s98, s67
	s_or_b32 s52, s31, 0x400000
	s_or_b32 s98, s67, 0x400000
	v_cmp_le_u32_e32 vcc, s52, v34
	v_cmp_le_u32_e64 s[100:101], s98, v38
	s_bcnt1_i32_b64 s51, vcc
	s_bcnt1_i32_b64 s99, s[100:101]
	s_cmp_ge_u32 s51, 16
	s_cselect_b32 s31, s52, s31
	s_cmp_ge_u32 s99, 16
	s_cselect_b32 s67, s98, s67
	s_or_b32 s52, s31, 0x200000
	s_or_b32 s98, s67, 0x200000
	v_cmp_le_u32_e32 vcc, s52, v34
	v_cmp_le_u32_e64 s[100:101], s98, v38
	s_bcnt1_i32_b64 s51, vcc
	s_bcnt1_i32_b64 s99, s[100:101]
	s_cmp_ge_u32 s51, 16
	s_cselect_b32 s31, s52, s31
	s_cmp_ge_u32 s99, 16
	s_cselect_b32 s67, s98, s67
	s_or_b32 s52, s31, 0x100000
	s_or_b32 s98, s67, 0x100000
	v_cmp_le_u32_e32 vcc, s52, v34
	v_cmp_le_u32_e64 s[100:101], s98, v38
	s_bcnt1_i32_b64 s51, vcc
	s_bcnt1_i32_b64 s99, s[100:101]
	s_cmp_ge_u32 s51, 16
	s_cselect_b32 s31, s52, s31
	s_cmp_ge_u32 s99, 16
	s_cselect_b32 s67, s98, s67
	s_or_b32 s52, s31, 0x80000
	s_or_b32 s98, s67, 0x80000
	v_cmp_le_u32_e32 vcc, s52, v34
	v_cmp_le_u32_e64 s[100:101], s98, v38
	s_bcnt1_i32_b64 s51, vcc
	s_bcnt1_i32_b64 s99, s[100:101]
	s_cmp_ge_u32 s51, 16
	s_cselect_b32 s31, s52, s31
	s_cmp_ge_u32 s99, 16
	s_cselect_b32 s67, s98, s67
	s_or_b32 s52, s31, 0x40000
	s_or_b32 s98, s67, 0x40000
	v_cmp_le_u32_e32 vcc, s52, v34
	v_cmp_le_u32_e64 s[100:101], s98, v38
	s_bcnt1_i32_b64 s51, vcc
	s_bcnt1_i32_b64 s99, s[100:101]
	s_cmp_ge_u32 s51, 16
	s_cselect_b32 s31, s52, s31
	s_cmp_ge_u32 s99, 16
	s_cselect_b32 s67, s98, s67
	s_or_b32 s52, s31, 0x20000
	s_or_b32 s98, s67, 0x20000
	v_cmp_le_u32_e32 vcc, s52, v34
	v_cmp_le_u32_e64 s[100:101], s98, v38
	s_bcnt1_i32_b64 s51, vcc
	s_bcnt1_i32_b64 s99, s[100:101]
	s_cmp_ge_u32 s51, 16
	s_cselect_b32 s31, s52, s31
	s_cmp_ge_u32 s99, 16
	s_cselect_b32 s67, s98, s67
	s_or_b32 s52, s31, 0x10000
	s_or_b32 s98, s67, 0x10000
	v_cmp_le_u32_e32 vcc, s52, v34
	v_cmp_le_u32_e64 s[100:101], s98, v38
	s_bcnt1_i32_b64 s51, vcc
	s_bcnt1_i32_b64 s99, s[100:101]
	s_cmp_ge_u32 s51, 16
	s_cselect_b32 s31, s52, s31
	s_cmp_ge_u32 s99, 16
	s_cselect_b32 s67, s98, s67
	s_or_b32 s52, s31, 0x8000
	s_or_b32 s98, s67, 0x8000
; #define LAS __attribute__((address_space(3)))
; DI void nsa_unit(LAS char* lds, int b, int g, int qb, const bf16* Z, const bf16* KC, const bf16* VC, bf16* On, int tid, int lane, int wave) {
;     ...
;             int cnt = 0;
; #pragma unroll 4
;             for (int m4 = 0; m4 < 16; ++m4) {
;                 const f32x4 vm = *(const LAS f32x4*)(vs + 4 * m4);
; #pragma unroll
;                 for (int e = 0; e < 4; ++e) { const int m = 4 * m4 + e; cnt += (vm[e] > v || (vm[e] == v && m < n)) ? 1 : 0; }
;             }
;             const bool sel = (cnt < 16) && (n <= qb);
;             const unsigned long long mk = __ballot(sel);
;             if (lane == 0) selm[q] = mk;
	v_cmp_le_u32_e32 vcc, s52, v34
	v_cmp_le_u32_e64 s[100:101], s98, v38
	s_bcnt1_i32_b64 s51, vcc
	s_bcnt1_i32_b64 s99, s[100:101]
	s_cmp_ge_u32 s51, 16
	s_cselect_b32 s31, s52, s31
	s_cmp_ge_u32 s99, 16
	s_cselect_b32 s67, s98, s67
	s_or_b32 s52, s31, 0x4000
	s_or_b32 s98, s67, 0x4000
	v_cmp_le_u32_e32 vcc, s52, v34
	v_cmp_le_u32_e64 s[100:101], s98, v38
	s_bcnt1_i32_b64 s51, vcc
	s_bcnt1_i32_b64 s99, s[100:101]
	s_cmp_ge_u32 s51, 16
	s_cselect_b32 s31, s52, s31
	s_cmp_ge_u32 s99, 16
	s_cselect_b32 s67, s98, s67
	s_or_b32 s52, s31, 0x2000
	s_or_b32 s98, s67, 0x2000
	v_cmp_le_u32_e32 vcc, s52, v34
	v_cmp_le_u32_e64 s[100:101], s98, v38
	s_bcnt1_i32_b64 s51, vcc
	s_bcnt1_i32_b64 s99, s[100:101]
	s_cmp_ge_u32 s51, 16
	s_cselect_b32 s31, s52, s31
	s_cmp_ge_u32 s99, 16
	s_cselect_b32 s67, s98, s67
	s_or_b32 s52, s31, 0x1000
	s_or_b32 s98, s67, 0x1000
	v_cmp_le_u32_e32 vcc, s52, v34
	v_cmp_le_u32_e64 s[100:101], s98, v38
	s_bcnt1_i32_b64 s51, vcc
	s_bcnt1_i32_b64 s99, s[100:101]
	s_cmp_ge_u32 s51, 16
	s_cselect_b32 s31, s52, s31
	s_cmp_ge_u32 s99, 16
	s_cselect_b32 s67, s98, s67
	s_or_b32 s52, s31, 0x800
	s_or_b32 s98, s67, 0x800
	v_cmp_le_u32_e32 vcc, s52, v34
	v_cmp_le_u32_e64 s[100:101], s98, v38
	s_bcnt1_i32_b64 s51, vcc
	s_bcnt1_i32_b64 s99, s[100:101]
	s_cmp_ge_u32 s51, 16
	s_cselect_b32 s31, s52, s31
	s_cmp_ge_u32 s99, 16
	s_cselect_b32 s67, s98, s67
	s_or_b32 s52, s31, 0x400
	s_or_b32 s98, s67, 0x400
	v_cmp_le_u32_e32 vcc, s52, v34
	v_cmp_le_u32_e64 s[100:101], s98, v38
	s_bcnt1_i32_b64 s51, vcc
	s_bcnt1_i32_b64 s99, s[100:101]
	s_cmp_ge_u32 s51, 16
	s_cselect_b32 s31, s52, s31
	s_cmp_ge_u32 s99, 16
	s_cselect_b32 s67, s98, s67
	s_or_b32 s52, s31, 0x200
	s_or_b32 s98, s67, 0x200
	v_cmp_le_u32_e32 vcc, s52, v34
	v_cmp_le_u32_e64 s[100:101], s98, v38
	s_bcnt1_i32_b64 s51, vcc
	s_bcnt1_i32_b64 s99, s[100:101]
	s_cmp_ge_u32 s51, 16
	s_cselect_b32 s31, s52, s31
	s_cmp_ge_u32 s99, 16
	s_cselect_b32 s67, s98, s67
	s_or_b32 s52, s31, 0x100
	s_or_b32 s98, s67, 0x100
	v_cmp_le_u32_e32 vcc, s52, v34
	v_cmp_le_u32_e64 s[100:101], s98, v38
	s_bcnt1_i32_b64 s51, vcc
	s_bcnt1_i32_b64 s99, s[100:101]
	s_cmp_ge_u32 s51, 16
	s_cselect_b32 s31, s52, s31
	s_cmp_ge_u32 s99, 16
	s_cselect_b32 s67, s98, s67
	s_or_b32 s52, s31, 0x80
	s_or_b32 s98, s67, 0x80
	v_cmp_le_u32_e32 vcc, s52, v34
	v_cmp_le_u32_e64 s[100:101], s98, v38
	s_bcnt1_i32_b64 s51, vcc
	s_bcnt1_i32_b64 s99, s[100:101]
	s_cmp_ge_u32 s51, 16
	s_cselect_b32 s31, s52, s31
	s_cmp_ge_u32 s99, 16
	s_cselect_b32 s67, s98, s67
	s_or_b32 s52, s31, 64
	s_or_b32 s98, s67, 64
	v_cmp_le_u32_e32 vcc, s52, v34
	v_cmp_le_u32_e64 s[100:101], s98, v38
	s_bcnt1_i32_b64 s51, vcc
	s_bcnt1_i32_b64 s99, s[100:101]
	s_cmp_ge_u32 s51, 16
	s_cselect_b32 s31, s52, s31
	s_cmp_ge_u32 s99, 16
	s_cselect_b32 s67, s98, s67
	s_or_b32 s52, s31, 32
	s_or_b32 s98, s67, 32
	v_cmp_le_u32_e32 vcc, s52, v34
	v_cmp_le_u32_e64 s[100:101], s98, v38
	s_bcnt1_i32_b64 s51, vcc
	s_bcnt1_i32_b64 s99, s[100:101]
	s_cmp_ge_u32 s51, 16
	s_cselect_b32 s31, s52, s31
	s_cmp_ge_u32 s99, 16
	s_cselect_b32 s67, s98, s67
	s_or_b32 s52, s31, 16
	s_or_b32 s98, s67, 16
	v_cmp_le_u32_e32 vcc, s52, v34
	v_cmp_le_u32_e64 s[100:101], s98, v38
	s_bcnt1_i32_b64 s51, vcc
	s_bcnt1_i32_b64 s99, s[100:101]
	s_cmp_ge_u32 s51, 16
	s_cselect_b32 s31, s52, s31
	s_cmp_ge_u32 s99, 16
	s_cselect_b32 s67, s98, s67
	s_or_b32 s52, s31, 8
	s_or_b32 s98, s67, 8
	v_cmp_le_u32_e32 vcc, s52, v34
	v_cmp_le_u32_e64 s[100:101], s98, v38
	s_bcnt1_i32_b64 s51, vcc
	s_bcnt1_i32_b64 s99, s[100:101]
	s_cmp_ge_u32 s51, 16
	s_cselect_b32 s31, s52, s31
	s_cmp_ge_u32 s99, 16
	s_cselect_b32 s67, s98, s67
	s_or_b32 s52, s31, 4
	s_or_b32 s98, s67, 4
	v_cmp_le_u32_e32 vcc, s52, v34
	v_cmp_le_u32_e64 s[100:101], s98, v38
	s_bcnt1_i32_b64 s51, vcc
	s_bcnt1_i32_b64 s99, s[100:101]
	s_cmp_ge_u32 s51, 16
	s_cselect_b32 s31, s52, s31
	s_cmp_ge_u32 s99, 16
	s_cselect_b32 s67, s98, s67
	s_or_b32 s52, s31, 2
	s_or_b32 s98, s67, 2
	v_cmp_le_u32_e32 vcc, s52, v34
	v_cmp_le_u32_e64 s[100:101], s98, v38
	s_bcnt1_i32_b64 s51, vcc
	s_bcnt1_i32_b64 s99, s[100:101]
	s_cmp_ge_u32 s51, 16
	s_cselect_b32 s31, s52, s31
	s_cmp_ge_u32 s99, 16
	s_cselect_b32 s67, s98, s67
	s_or_b32 s52, s31, 1
	s_or_b32 s98, s67, 1
	v_cmp_le_u32_e32 vcc, s52, v34
	v_cmp_le_u32_e64 s[100:101], s98, v38
	s_bcnt1_i32_b64 s51, vcc
	s_bcnt1_i32_b64 s99, s[100:101]
	s_cmp_ge_u32 s51, 16
	s_cselect_b32 s31, s52, s31
	s_cmp_ge_u32 s99, 16
	s_cselect_b32 s67, s98, s67
	v_cmp_lt_u32_e32 vcc, s31, v34
	s_bcnt1_i32_b64 s51, vcc
	s_mov_b64 s[20:21], vcc
	v_cmp_eq_u32_e64 s[18:19], s31, v34
	s_sub_i32 s51, 16, s51
	s_nop 0
	v_mbcnt_lo_u32_b32 v35, s18, 0
	v_mbcnt_hi_u32_b32 v35, s19, v35
	v_cmp_gt_u32_e32 vcc, s51, v35
	s_and_b64 s[18:19], s[18:19], vcc
	s_or_b64 s[20:21], s[20:21], s[18:19]
	s_and_b64 s[20:21], s[20:21], s[16:17]
	v_cmp_lt_u32_e32 vcc, s67, v38
	s_bcnt1_i32_b64 s51, vcc
	s_mov_b64 s[100:101], vcc
	v_cmp_eq_u32_e64 s[18:19], s67, v38
	s_sub_i32 s51, 16, s51
	s_nop 0
	v_mbcnt_lo_u32_b32 v35, s18, 0
	v_mbcnt_hi_u32_b32 v35, s19, v35
	v_cmp_gt_u32_e32 vcc, s51, v35
	s_and_b64 s[18:19], s[18:19], vcc
	s_or_b64 s[100:101], s[100:101], s[18:19]
	s_and_b64 s[100:101], s[100:101], s[16:17]
	s_and_saveexec_b64 s[18:19], s[40:41]
	s_cbranch_execz .Ltk_latch
	s_lshl_b32 s30, s30, 3
	s_add_i32 s30, s30, 0x1c000
	v_mov_b32_e32 v0, s30
	v_mov_b64_e32 v[34:35], s[20:21]
	v_mov_b64_e32 v[38:39], s[100:101]
	ds_write_b64 v0, v[34:35]
	ds_write_b64 v0, v[38:39] offset:8
.Ltk_latch:
	s_or_b64 exec, exec, s[18:19]
	s_add_i32 s29, s29, 2
	s_cmp_eq_u32 s29, 8
	s_cbranch_scc0 .LBB0_1084
